# baseline (speedup 1.0000x reference)
; __device__ __forceinline__ void stg16f(void* p, float a, float b, float c, float d) { typedef float f32x4_ __attribute__((ext_vector_type(4))); const f32x4_ v = {a, b, c, d}; *(__attribute__((address_space(1))) f32x4_*)(p) = v; }
; __device__ __forceinline__ float4 ldg16f(const void* p) { typedef float f32x4_ __attribute__((ext_vector_type(4))); const f32x4_ v = *(const __attribute__((address_space(1))) f32x4_*)(p); return make_float4(v.x, v.y, v.z, v.w); }
; #define EPI_LOOP(...) _Pragma("unroll") for (int ai = 0; ai < 2; ++ai) _Pragma("unroll") for (int bj = 0; bj < 2; ++bj) \
;     _Pragma("unroll") for (int m = 0; m < 4; ++m) _Pragma("unroll") for (int n = 0; n < 2; ++n) { \
;       const int o = toff + (ai * HALF + m * 16) * ld + bj * HALF + n * 16; const f32x4 v = acc[ai][bj][m][n]; __VA_ARGS__ }
; template <class EPIF>
; __device__ __forceinline__ void gemm_stream(const u16* __restrict__ A, const u16* __restrict__ Bt, const int K, const int nM,
;                                             const int nN, const int loc, const int G, EPIF epif, u16* shm, const int wv) {
;     ...
;         float* d = (float*)ep.dst + (long)brow * ld + ccol;
;         const float* r = ep.res + (long)brow * ld + ccol;
;         EPI_LOOP({ const float4 rv = ldg16f(r + o); stg16f(d + o, rv.x + v[0], rv.y + v[1], rv.z + v[2], rv.w + v[3]); })
.LBB0_293:
	s_lshl_b64 s[8:9], s[24:25], 2
	s_lshl_b64 s[10:11], s[22:23], 2
	s_waitcnt vmcnt(0) lgkmcnt(0)
	v_lshl_add_u64 v[152:153], v[134:135], 0, s[8:9]
	v_lshl_add_u64 v[150:151], v[146:147], 0, s[8:9]
	v_lshl_add_u64 v[152:153], v[152:153], 0, s[10:11]
	v_lshl_add_u64 v[150:151], v[150:151], 0, s[10:11]
	s_lshl_b32 s8, s83, 4
	s_lshl_b32 s9, s83, 7
	s_mov_b32 s10, 0
	v_add_u32_e32 v182, s10, v148
	v_ashrrev_i32_e32 v183, 31, v182
	v_lshlrev_b64 v[182:183], 2, v[182:183]
	v_lshl_add_u64 v[174:175], v[152:153], 0, v[182:183]
	global_load_dwordx4 v[186:189], v[174:175], off nt
	global_load_dwordx4 v[190:193], v[174:175], off offset:64 nt
	global_load_dwordx4 v[194:197], v[174:175], off offset:512 nt
	global_load_dwordx4 v[198:201], v[174:175], off offset:576 nt
	s_mul_i32 s10, s8, 1
	v_add_u32_e32 v182, s10, v148
	v_ashrrev_i32_e32 v183, 31, v182
	v_lshlrev_b64 v[182:183], 2, v[182:183]
	v_lshl_add_u64 v[174:175], v[152:153], 0, v[182:183]
	global_load_dwordx4 v[202:205], v[174:175], off nt
	global_load_dwordx4 v[206:209], v[174:175], off offset:64 nt
	global_load_dwordx4 v[216:219], v[174:175], off offset:512 nt
	global_load_dwordx4 v[220:223], v[174:175], off offset:576 nt
	s_mov_b32 s10, 0
	v_add_u32_e32 v182, s10, v148
	v_ashrrev_i32_e32 v183, 31, v182
	v_lshlrev_b64 v[182:183], 2, v[182:183]
	v_lshl_add_u64 v[176:177], v[150:151], 0, v[182:183]
	s_mul_i32 s10, s8, 2
	v_add_u32_e32 v182, s10, v148
	v_ashrrev_i32_e32 v183, 31, v182
	v_lshlrev_b64 v[182:183], 2, v[182:183]
	v_lshl_add_u64 v[174:175], v[152:153], 0, v[182:183]
	s_waitcnt vmcnt(7)
	v_pk_add_f32 v[186:187], v[124:125], v[186:187]
	v_pk_add_f32 v[188:189], v[126:127], v[188:189]
	global_store_dwordx4 v[176:177], v[186:189], off
	global_load_dwordx4 v[186:189], v[174:175], off nt
	s_waitcnt vmcnt(8)
	v_pk_add_f32 v[190:191], v[120:121], v[190:191]
	v_pk_add_f32 v[192:193], v[122:123], v[192:193]
	global_store_dwordx4 v[176:177], v[190:193], off offset:64
	global_load_dwordx4 v[190:193], v[174:175], off offset:64 nt
	s_waitcnt vmcnt(9)
	v_pk_add_f32 v[194:195], v[108:109], v[194:195]
	v_pk_add_f32 v[196:197], v[110:111], v[196:197]
	global_store_dwordx4 v[176:177], v[194:197], off offset:512
	global_load_dwordx4 v[194:197], v[174:175], off offset:512 nt
	s_waitcnt vmcnt(10)
	v_pk_add_f32 v[198:199], v[104:105], v[198:199]
	v_pk_add_f32 v[200:201], v[106:107], v[200:201]
	global_store_dwordx4 v[176:177], v[198:201], off offset:576
	global_load_dwordx4 v[198:201], v[174:175], off offset:576 nt
	s_mul_i32 s10, s8, 1
	v_add_u32_e32 v182, s10, v148
	v_ashrrev_i32_e32 v183, 31, v182
	v_lshlrev_b64 v[182:183], 2, v[182:183]
	v_lshl_add_u64 v[176:177], v[150:151], 0, v[182:183]
	s_mul_i32 s10, s8, 3
	v_add_u32_e32 v182, s10, v148
	v_ashrrev_i32_e32 v183, 31, v182
	v_lshlrev_b64 v[182:183], 2, v[182:183]
	v_lshl_add_u64 v[174:175], v[152:153], 0, v[182:183]
	s_waitcnt vmcnt(11)
	v_pk_add_f32 v[202:203], v[116:117], v[202:203]
	v_pk_add_f32 v[204:205], v[118:119], v[204:205]
	global_store_dwordx4 v[176:177], v[202:205], off
	global_load_dwordx4 v[202:205], v[174:175], off nt
	s_waitcnt vmcnt(12)
	v_pk_add_f32 v[206:207], v[112:113], v[206:207]
	v_pk_add_f32 v[208:209], v[114:115], v[208:209]
	global_store_dwordx4 v[176:177], v[206:209], off offset:64
	global_load_dwordx4 v[206:209], v[174:175], off offset:64 nt
	s_waitcnt vmcnt(13)
	v_pk_add_f32 v[216:217], v[92:93], v[216:217]
	v_pk_add_f32 v[218:219], v[94:95], v[218:219]
	global_store_dwordx4 v[176:177], v[216:219], off offset:512
	global_load_dwordx4 v[216:219], v[174:175], off offset:512 nt
	s_waitcnt vmcnt(14)
	v_pk_add_f32 v[220:221], v[88:89], v[220:221]
	v_pk_add_f32 v[222:223], v[90:91], v[222:223]
	global_store_dwordx4 v[176:177], v[220:223], off offset:576
	global_load_dwordx4 v[220:223], v[174:175], off offset:576 nt
	s_mul_i32 s10, s8, 2
	v_add_u32_e32 v182, s10, v148
	v_ashrrev_i32_e32 v183, 31, v182
	v_lshlrev_b64 v[182:183], 2, v[182:183]
	v_lshl_add_u64 v[176:177], v[150:151], 0, v[182:183]
	s_mov_b32 s10, 0
	s_add_i32 s10, s10, s9
	v_add_u32_e32 v182, s10, v148
	v_ashrrev_i32_e32 v183, 31, v182
	v_lshlrev_b64 v[182:183], 2, v[182:183]
	v_lshl_add_u64 v[174:175], v[152:153], 0, v[182:183]
	s_waitcnt vmcnt(14)
	v_pk_add_f32 v[186:187], v[100:101], v[186:187]
	v_pk_add_f32 v[188:189], v[102:103], v[188:189]
	global_store_dwordx4 v[176:177], v[186:189], off
	global_load_dwordx4 v[186:189], v[174:175], off nt
	s_waitcnt vmcnt(14)
	v_pk_add_f32 v[190:191], v[96:97], v[190:191]
	v_pk_add_f32 v[192:193], v[98:99], v[192:193]
	global_store_dwordx4 v[176:177], v[190:193], off offset:64
	global_load_dwordx4 v[190:193], v[174:175], off offset:64 nt
	s_waitcnt vmcnt(14)
	v_pk_add_f32 v[194:195], v[72:73], v[194:195]
	v_pk_add_f32 v[196:197], v[74:75], v[196:197]
	global_store_dwordx4 v[176:177], v[194:197], off offset:512
	global_load_dwordx4 v[194:197], v[174:175], off offset:512 nt
	s_waitcnt vmcnt(14)
	v_pk_add_f32 v[198:199], v[64:65], v[198:199]
	v_pk_add_f32 v[200:201], v[66:67], v[200:201]
	global_store_dwordx4 v[176:177], v[198:201], off offset:576
	global_load_dwordx4 v[198:201], v[174:175], off offset:576 nt
	s_mul_i32 s10, s8, 3
	v_add_u32_e32 v182, s10, v148
	v_ashrrev_i32_e32 v183, 31, v182
	v_lshlrev_b64 v[182:183], 2, v[182:183]
	v_lshl_add_u64 v[176:177], v[150:151], 0, v[182:183]
	s_mul_i32 s10, s8, 1
	s_add_i32 s10, s10, s9
	v_add_u32_e32 v182, s10, v148
	v_ashrrev_i32_e32 v183, 31, v182
	v_lshlrev_b64 v[182:183], 2, v[182:183]
	v_lshl_add_u64 v[174:175], v[152:153], 0, v[182:183]
	s_waitcnt vmcnt(14)
; __device__ __forceinline__ void stg16f(void* p, float a, float b, float c, float d) { typedef float f32x4_ __attribute__((ext_vector_type(4))); const f32x4_ v = {a, b, c, d}; *(__attribute__((address_space(1))) f32x4_*)(p) = v; }
; __device__ __forceinline__ float4 ldg16f(const void* p) { typedef float f32x4_ __attribute__((ext_vector_type(4))); const f32x4_ v = *(const __attribute__((address_space(1))) f32x4_*)(p); return make_float4(v.x, v.y, v.z, v.w); }
; #define EPI_LOOP(...) _Pragma("unroll") for (int ai = 0; ai < 2; ++ai) _Pragma("unroll") for (int bj = 0; bj < 2; ++bj) \
;     _Pragma("unroll") for (int m = 0; m < 4; ++m) _Pragma("unroll") for (int n = 0; n < 2; ++n) { \
;       const int o = toff + (ai * HALF + m * 16) * ld + bj * HALF + n * 16; const f32x4 v = acc[ai][bj][m][n]; __VA_ARGS__ }
; template <class EPIF>
; __device__ __forceinline__ void gemm_stream(const u16* __restrict__ A, const u16* __restrict__ Bt, const int K, const int nM,
;                                             const int nN, const int loc, const int G, EPIF epif, u16* shm, const int wv) {
;     ...
;         float* d = (float*)ep.dst + (long)brow * ld + ccol;
;         const float* r = ep.res + (long)brow * ld + ccol;
;         EPI_LOOP({ const float4 rv = ldg16f(r + o); stg16f(d + o, rv.x + v[0], rv.y + v[1], rv.z + v[2], rv.w + v[3]); })
	v_pk_add_f32 v[202:203], v[84:85], v[202:203]
	v_pk_add_f32 v[204:205], v[86:87], v[204:205]
	global_store_dwordx4 v[176:177], v[202:205], off
	global_load_dwordx4 v[202:205], v[174:175], off nt
	s_waitcnt vmcnt(14)
	v_pk_add_f32 v[206:207], v[80:81], v[206:207]
	v_pk_add_f32 v[208:209], v[82:83], v[208:209]
	global_store_dwordx4 v[176:177], v[206:209], off offset:64
	global_load_dwordx4 v[206:209], v[174:175], off offset:64 nt
	s_waitcnt vmcnt(14)
	v_pk_add_f32 v[216:217], v[56:57], v[216:217]
	v_pk_add_f32 v[218:219], v[58:59], v[218:219]
	global_store_dwordx4 v[176:177], v[216:219], off offset:512
	global_load_dwordx4 v[216:219], v[174:175], off offset:512 nt
	s_waitcnt vmcnt(14)
	v_pk_add_f32 v[220:221], v[48:49], v[220:221]
	v_pk_add_f32 v[222:223], v[50:51], v[222:223]
	global_store_dwordx4 v[176:177], v[220:223], off offset:576
	global_load_dwordx4 v[220:223], v[174:175], off offset:576 nt
	s_mov_b32 s10, 0
	s_add_i32 s10, s10, s9
	v_add_u32_e32 v182, s10, v148
	v_ashrrev_i32_e32 v183, 31, v182
	v_lshlrev_b64 v[182:183], 2, v[182:183]
	v_lshl_add_u64 v[176:177], v[150:151], 0, v[182:183]
	s_mul_i32 s10, s8, 2
	s_add_i32 s10, s10, s9
	v_add_u32_e32 v182, s10, v148
	v_ashrrev_i32_e32 v183, 31, v182
	v_lshlrev_b64 v[182:183], 2, v[182:183]
	v_lshl_add_u64 v[174:175], v[152:153], 0, v[182:183]
	s_waitcnt vmcnt(14)
	v_pk_add_f32 v[186:187], v[76:77], v[186:187]
	v_pk_add_f32 v[188:189], v[78:79], v[188:189]
	global_store_dwordx4 v[176:177], v[186:189], off
	global_load_dwordx4 v[186:189], v[174:175], off nt
	s_waitcnt vmcnt(14)
	v_pk_add_f32 v[190:191], v[68:69], v[190:191]
	v_pk_add_f32 v[192:193], v[70:71], v[192:193]
	global_store_dwordx4 v[176:177], v[190:193], off offset:64
	global_load_dwordx4 v[190:193], v[174:175], off offset:64 nt
	s_waitcnt vmcnt(14)
	v_pk_add_f32 v[194:195], v[36:37], v[194:195]
	v_pk_add_f32 v[196:197], v[38:39], v[196:197]
	global_store_dwordx4 v[176:177], v[194:197], off offset:512
	global_load_dwordx4 v[194:197], v[174:175], off offset:512 nt
	s_waitcnt vmcnt(14)
	v_pk_add_f32 v[198:199], v[32:33], v[198:199]
	v_pk_add_f32 v[200:201], v[34:35], v[200:201]
	global_store_dwordx4 v[176:177], v[198:201], off offset:576
	global_load_dwordx4 v[198:201], v[174:175], off offset:576 nt
	s_mul_i32 s10, s8, 1
	s_add_i32 s10, s10, s9
	v_add_u32_e32 v182, s10, v148
	v_ashrrev_i32_e32 v183, 31, v182
	v_lshlrev_b64 v[182:183], 2, v[182:183]
	v_lshl_add_u64 v[176:177], v[150:151], 0, v[182:183]
	s_mul_i32 s10, s8, 3
	s_add_i32 s10, s10, s9
	v_add_u32_e32 v182, s10, v148
	v_ashrrev_i32_e32 v183, 31, v182
	v_lshlrev_b64 v[182:183], 2, v[182:183]
	v_lshl_add_u64 v[174:175], v[152:153], 0, v[182:183]
	s_waitcnt vmcnt(14)
	v_pk_add_f32 v[202:203], v[60:61], v[202:203]
	v_pk_add_f32 v[204:205], v[62:63], v[204:205]
	global_store_dwordx4 v[176:177], v[202:205], off
	global_load_dwordx4 v[202:205], v[174:175], off nt
	s_waitcnt vmcnt(14)
	v_pk_add_f32 v[206:207], v[52:53], v[206:207]
	v_pk_add_f32 v[208:209], v[54:55], v[208:209]
	global_store_dwordx4 v[176:177], v[206:209], off offset:64
	global_load_dwordx4 v[206:209], v[174:175], off offset:64 nt
	s_waitcnt vmcnt(14)
	v_pk_add_f32 v[216:217], v[20:21], v[216:217]
	v_pk_add_f32 v[218:219], v[22:23], v[218:219]
	global_store_dwordx4 v[176:177], v[216:219], off offset:512
	global_load_dwordx4 v[216:219], v[174:175], off offset:512 nt
	s_waitcnt vmcnt(14)
	v_pk_add_f32 v[220:221], v[16:17], v[220:221]
	v_pk_add_f32 v[222:223], v[18:19], v[222:223]
	global_store_dwordx4 v[176:177], v[220:223], off offset:576
	global_load_dwordx4 v[220:223], v[174:175], off offset:576 nt
	s_mul_i32 s10, s8, 2
	s_add_i32 s10, s10, s9
	v_add_u32_e32 v182, s10, v148
	v_ashrrev_i32_e32 v183, 31, v182
	v_lshlrev_b64 v[182:183], 2, v[182:183]
	v_lshl_add_u64 v[176:177], v[150:151], 0, v[182:183]
	s_waitcnt vmcnt(14)
	v_pk_add_f32 v[186:187], v[44:45], v[186:187]
	v_pk_add_f32 v[188:189], v[46:47], v[188:189]
	global_store_dwordx4 v[176:177], v[186:189], off
	s_waitcnt vmcnt(13)
	v_pk_add_f32 v[190:191], v[40:41], v[190:191]
	v_pk_add_f32 v[192:193], v[42:43], v[192:193]
	global_store_dwordx4 v[176:177], v[190:193], off offset:64
	s_waitcnt vmcnt(12)
	v_pk_add_f32 v[194:195], v[12:13], v[194:195]
	v_pk_add_f32 v[196:197], v[14:15], v[196:197]
	global_store_dwordx4 v[176:177], v[194:197], off offset:512
	s_waitcnt vmcnt(11)
	v_pk_add_f32 v[198:199], v[8:9], v[198:199]
	v_pk_add_f32 v[200:201], v[10:11], v[200:201]
	global_store_dwordx4 v[176:177], v[198:201], off offset:576
	s_mul_i32 s10, s8, 3
	s_add_i32 s10, s10, s9
	v_add_u32_e32 v182, s10, v148
	v_ashrrev_i32_e32 v183, 31, v182
	v_lshlrev_b64 v[182:183], 2, v[182:183]
	v_lshl_add_u64 v[176:177], v[150:151], 0, v[182:183]
	s_waitcnt vmcnt(10)
	v_pk_add_f32 v[202:203], v[28:29], v[202:203]
	v_pk_add_f32 v[204:205], v[30:31], v[204:205]
	global_store_dwordx4 v[176:177], v[202:205], off
	s_waitcnt vmcnt(9)
	v_pk_add_f32 v[206:207], v[24:25], v[206:207]
	v_pk_add_f32 v[208:209], v[26:27], v[208:209]
	global_store_dwordx4 v[176:177], v[206:209], off offset:64
	s_waitcnt vmcnt(8)
	v_pk_add_f32 v[216:217], v[4:5], v[216:217]
	v_pk_add_f32 v[218:219], v[6:7], v[218:219]
	global_store_dwordx4 v[176:177], v[216:219], off offset:512
	s_waitcnt vmcnt(7)
	v_pk_add_f32 v[220:221], v[0:1], v[220:221]
	v_pk_add_f32 v[222:223], v[2:3], v[222:223]
	global_store_dwordx4 v[176:177], v[220:223], off offset:576
	s_cbranch_execnz .LBB0_185
